# stack on v129: bias-table reload skipped for non-first attention units; last-layer norm loop issues a row's 8 loads together (counted waits)
# baseline (speedup 1.0000x reference)
; #define LAS __attribute__((address_space(3)))
; template <int DV, int NMAP> ...
;     ...
;     if (tid < 256) ((LAS float*)(lds + TAB_OFF))[tid] = (tid < 255) ? tabg[tid] : 0.f;
; __global__ void __launch_bounds__(512, 2) trunk_fwd(Args a) {
;     ...
;                 for (int u = u0; u < 128 * 8; u += G) {
;                     const int h = u & 7, j = u >> 3, ii = j & 31, r = j >> 5;
.LBB0_306:
	s_lshl_b32 s4, s22, 8
	s_and_b32 s36, s4, 0x700
	v_mov_b32_e32 v0, v230
	s_movk_i32 s4, 0x100
	s_nop 0
	v_readfirstlane_b32 s20, v0
	v_cmp_gt_i32_e32 vcc, s4, v0
	s_cmpk_lt_u32 s22, 0x100
	s_cbranch_scc1 .Ltabb
	s_mov_b64 vcc, 0
.Ltabb:
	s_and_saveexec_b64 s[4:5], vcc
	s_cbranch_execz .LBB0_310
	s_movk_i32 s6, 0xff
	v_cmp_ne_u32_e32 vcc, s6, v0
	v_mov_b32_e32 v1, 0
	s_and_saveexec_b64 s[6:7], vcc
	s_cbranch_execz .LBB0_309
	s_lshl_b32 s8, s36, 2
	s_add_u32 s8, s94, s8
	s_addc_u32 s9, s95, 0
	v_ashrrev_i32_e32 v1, 31, v0
	v_lshl_add_u64 v[2:3], v[0:1], 2, s[8:9]
	global_load_dword v1, v[2:3], off

; #define LAS __attribute__((address_space(3)))
; template <int DV, int NMAP> ...
;     ...
;     if (tid < 256) ((LAS float*)(lds + TAB_OFF))[tid] = (tid < 255) ? tabg[tid] : 0.f;
; __global__ void __launch_bounds__(512, 2) trunk_fwd(Args a) {
;     ...
;                 for (int u = u0; u < 64 * 16; u += G) {
;                     const int h = u & 15, qblk = u >> 4, c0 = 4 * qblk;
;     ...
;                     att::attn_unit<128, 1>(lds, QK, VT, OB, 256 * qblk, h, 128 * h, (c0 - 8 > 0 ? c0 - 8 : 0), c0 + 3, true, tabA + h * 256, 0.f, 1.f, nullptr);
.LBB0_336:
	v_mov_b32_e32 v96, v230
	s_movk_i32 s6, 0x100
	s_and_b32 s10, s75, 15
	s_nop 0
	v_readfirstlane_b32 s38, v96
	v_cmp_gt_i32_e32 vcc, s6, v96
	s_cmpk_lt_u32 s75, 0x100
	s_cbranch_scc1 .Ltaba
	s_mov_b64 vcc, 0
.Ltaba:
	s_and_saveexec_b64 s[6:7], vcc
	s_cbranch_execz .LBB0_340
	s_movk_i32 s8, 0xff
	v_cmp_ne_u32_e32 vcc, s8, v96
	v_mov_b32_e32 v0, 0
	s_and_saveexec_b64 s[8:9], vcc
	s_cbranch_execz .LBB0_339
	s_lshl_b32 s11, s10, 10
	s_add_u32 s16, s20, s11
	s_addc_u32 s17, s21, 0
	v_ashrrev_i32_e32 v97, 31, v96
	v_lshl_add_u64 v[0:1], v[96:97], 2, s[16:17]
	global_load_dword v0, v[0:1], off

; template <bool HIN_BF16, bool HOUT_BF16>
; __device__ __forceinline__ void norm_rows(const bf16* __restrict__ Y, const void* Hin, void* H, const float* __restrict__ gpost, float* __restrict__ RSout, int gw, int NGW, int lane) {
;     ...
;         if (HIN_BF16) {
; #pragma unroll
;             for (int j = 0; j < 4; ++j) { const v4u w = *(const v4u*)((const bf16*)Hin + (size_t)m * DM + 512 * j + 8 * lane);
;                 h[2 * j] = (f32x4){bf_lo(w[0]), bf_hi(w[0]), bf_lo(w[1]), bf_hi(w[1])}; h[2 * j + 1] = (f32x4){bf_lo(w[2]), bf_hi(w[2]), bf_lo(w[3]), bf_hi(w[3])}; }
;         } else {
;             const float* hr = (const float*)Hin + (size_t)m * DM + 8 * lane;
; #pragma unroll
;             for (int j = 0; j < 4; ++j) { h[2 * j] = *(const f32x4*)(hr + 512 * j); h[2 * j + 1] = *(const f32x4*)(hr + 512 * j + 4); }
;         }
;         if (Y) {
;             v4u y[4]; float ss = 0.f;
; #pragma unroll
;             for (int j = 0; j < 4; ++j) y[j] = *(const v4u*)(Y + (size_t)m * DM + 512 * j + 8 * lane);
; #pragma unroll
;             for (int j = 0; j < 4; ++j)
; #pragma unroll
;                 for (int e = 0; e < 4; ++e) { const float a = bf_lo(y[j][e]), b = bf_hi(y[j][e]); ss += a * a + b * b; }
.LBB0_797:
	global_load_dwordx4 v[160:163], v[34:35], off offset:-3072
	s_brev_b32 s5, 63
	v_add_co_u32_e32 v62, vcc, s5, v34
	s_add_i32 s4, s4, s80
	global_load_dwordx4 v[164:167], v[34:35], off offset:-2048
	v_addc_co_u32_e32 v63, vcc, -1, v35, vcc
	s_cmp_ge_i32 s4, s96
	global_load_dwordx4 v[168:171], v[34:35], off offset:-1024
	global_load_dwordx4 v[172:175], v[34:35], off
	v_lshl_add_u64 v[34:35], v[34:35], 0, s[18:19]
	global_load_dwordx4 v[50:53], v[62:63], off offset:-3072
	global_load_dwordx4 v[54:57], v[62:63], off offset:-2048
	global_load_dwordx4 v[58:61], v[62:63], off offset:-1024
	s_nop 0
	global_load_dwordx4 v[62:65], v[62:63], off
	s_waitcnt vmcnt(7)
	v_lshlrev_b32_e32 v38, 16, v160
	v_and_b32_e32 v39, 0xffff0000, v160
	v_lshlrev_b32_e32 v42, 16, v161
	v_and_b32_e32 v43, 0xffff0000, v161
	v_lshlrev_b32_e32 v36, 16, v162
	v_and_b32_e32 v37, 0xffff0000, v162
	v_lshlrev_b32_e32 v40, 16, v163
	v_and_b32_e32 v41, 0xffff0000, v163
	s_waitcnt vmcnt(6)
	v_lshlrev_b32_e32 v66, 16, v164
	v_and_b32_e32 v67, 0xffff0000, v164
	v_lshlrev_b32_e32 v68, 16, v165
	v_and_b32_e32 v69, 0xffff0000, v165
	v_lshlrev_b32_e32 v70, 16, v166
	v_and_b32_e32 v71, 0xffff0000, v166
	v_lshlrev_b32_e32 v72, 16, v167
	v_and_b32_e32 v73, 0xffff0000, v167
	s_waitcnt vmcnt(5)
	v_lshlrev_b32_e32 v74, 16, v168
	v_and_b32_e32 v75, 0xffff0000, v168
	v_lshlrev_b32_e32 v76, 16, v169
	v_and_b32_e32 v77, 0xffff0000, v169
	v_lshlrev_b32_e32 v78, 16, v170
	v_and_b32_e32 v79, 0xffff0000, v170
	v_lshlrev_b32_e32 v80, 16, v171
	v_and_b32_e32 v81, 0xffff0000, v171
	s_waitcnt vmcnt(4)
	v_lshlrev_b32_e32 v82, 16, v172
	v_and_b32_e32 v83, 0xffff0000, v172
	v_lshlrev_b32_e32 v84, 16, v173
	v_and_b32_e32 v85, 0xffff0000, v173
	v_lshlrev_b32_e32 v86, 16, v174
	v_and_b32_e32 v87, 0xffff0000, v174
	v_lshlrev_b32_e32 v88, 16, v175
	v_and_b32_e32 v89, 0xffff0000, v175
	s_waitcnt vmcnt(3)
	v_lshlrev_b32_e32 v90, 16, v50
	v_and_b32_e32 v91, 0xffff0000, v50
	v_lshlrev_b32_e32 v50, 16, v51
	v_and_b32_e32 v51, 0xffff0000, v51
	v_mul_f32_e32 v92, v91, v91
	v_mul_f32_e32 v93, v51, v51
	v_fmac_f32_e32 v92, v90, v90
	v_fmac_f32_e32 v93, v50, v50
	v_add_f32_e32 v94, v92, v93
	v_and_b32_e32 v93, 0xffff0000, v52
	v_lshlrev_b32_e32 v92, 16, v52
	v_mul_f32_e32 v52, v93, v93
	v_fmac_f32_e32 v52, v92, v92
	v_and_b32_e32 v95, 0xffff0000, v53
	v_add_f32_e32 v52, v52, v94
	v_lshlrev_b32_e32 v94, 16, v53
	v_mul_f32_e32 v53, v95, v95
	v_fmac_f32_e32 v53, v94, v94
	s_waitcnt vmcnt(2)
	v_and_b32_e32 v97, 0xffff0000, v54
	v_add_f32_e32 v52, v53, v52
	v_lshlrev_b32_e32 v96, 16, v54
	v_mul_f32_e32 v53, v97, v97
	v_fmac_f32_e32 v53, v96, v96
	v_lshlrev_b32_e32 v54, 16, v55
	v_and_b32_e32 v55, 0xffff0000, v55
	v_add_f32_e32 v52, v53, v52
	v_mul_f32_e32 v53, v55, v55
	v_fmac_f32_e32 v53, v54, v54
	v_and_b32_e32 v99, 0xffff0000, v56
	v_add_f32_e32 v52, v53, v52
	v_lshlrev_b32_e32 v98, 16, v56
	v_mul_f32_e32 v53, v99, v99
	v_fmac_f32_e32 v53, v98, v98
	v_lshlrev_b32_e32 v56, 16, v57
	v_and_b32_e32 v57, 0xffff0000, v57
	v_add_f32_e32 v52, v53, v52
	v_mul_f32_e32 v53, v57, v57
	v_fmac_f32_e32 v53, v56, v56
	s_waitcnt vmcnt(1)
	v_and_b32_e32 v101, 0xffff0000, v58
	v_add_f32_e32 v52, v53, v52
	v_lshlrev_b32_e32 v100, 16, v58
	v_mul_f32_e32 v53, v101, v101
	v_fmac_f32_e32 v53, v100, v100
	v_lshlrev_b32_e32 v58, 16, v59
	v_and_b32_e32 v59, 0xffff0000, v59
	v_add_f32_e32 v52, v53, v52
	v_mul_f32_e32 v53, v59, v59
	v_fmac_f32_e32 v53, v58, v58
	v_and_b32_e32 v103, 0xffff0000, v60
	v_add_f32_e32 v52, v53, v52
	v_lshlrev_b32_e32 v102, 16, v60
	v_mul_f32_e32 v53, v103, v103
	v_fmac_f32_e32 v53, v102, v102
	v_and_b32_e32 v105, 0xffff0000, v61
	v_add_f32_e32 v52, v53, v52
	v_lshlrev_b32_e32 v104, 16, v61
	v_mul_f32_e32 v53, v105, v105
	v_fmac_f32_e32 v53, v104, v104
	s_waitcnt vmcnt(0)
; __device__ __forceinline__ unsigned pk2(float lo, float hi) { return f2bf(lo) | (f2bf(hi) << 16); }
; template <bool HIN_BF16, bool HOUT_BF16>
; __device__ __forceinline__ void norm_rows(const bf16* __restrict__ Y, const void* Hin, void* H, const float* __restrict__ gpost, float* __restrict__ RSout, int gw, int NGW, int lane) {
;     ...
;             const float rs = 1.0f / sqrtf(wave_sum(ss) * (1.0f / DM) + RMS_EPS);
; #pragma unroll
;             for (int j = 0; j < 4; ++j) { const f32x4 g0 = *(const f32x4*)(gpost + 512 * j + 8 * lane), g1 = *(const f32x4*)(gpost + 512 * j + 8 * lane + 4);
;                 f32x4 a = {bf_lo(y[j][0]), bf_hi(y[j][0]), bf_lo(y[j][1]), bf_hi(y[j][1])}, b = {bf_lo(y[j][2]), bf_hi(y[j][2]), bf_lo(y[j][3]), bf_hi(y[j][3])};
;                 h[2 * j] = h[2 * j] + a * g0 * rs; h[2 * j + 1] = h[2 * j + 1] + b * g1 * rs; }
;         }
;         if (HOUT_BF16) {
; #pragma unroll
;             for (int j = 0; j < 4; ++j) { v4u w; w.x = pk2(h[2 * j][0], h[2 * j][1]); w.y = pk2(h[2 * j][2], h[2 * j][3]); w.z = pk2(h[2 * j + 1][0], h[2 * j + 1][1]); w.w = pk2(h[2 * j + 1][2], h[2 * j + 1][3]);
;                 *(v4u*)((bf16*)H + (size_t)m * DM + 512 * j + 8 * lane) = w; }
;         } else { float* ho = (float*)H + (size_t)m * DM + 8 * lane;
; #pragma unroll
;             for (int j = 0; j < 4; ++j) { *(f32x4*)(ho + 512 * j) = h[2 * j]; *(f32x4*)(ho + 512 * j + 4) = h[2 * j + 1]; } }
	v_and_b32_e32 v107, 0xffff0000, v62
	v_add_f32_e32 v52, v53, v52
	v_lshlrev_b32_e32 v106, 16, v62
	v_mul_f32_e32 v53, v107, v107
	v_fmac_f32_e32 v53, v106, v106
	v_and_b32_e32 v109, 0xffff0000, v63
	v_add_f32_e32 v52, v53, v52
	v_lshlrev_b32_e32 v108, 16, v63
	v_mul_f32_e32 v53, v109, v109
	v_fmac_f32_e32 v53, v108, v108
	v_and_b32_e32 v113, 0xffff0000, v65
	v_and_b32_e32 v112, 0xffff0000, v64
	v_add_f32_e32 v60, v53, v52
	v_lshlrev_b32_e32 v111, 16, v65
	v_lshlrev_b32_e32 v110, 16, v64
	v_pk_mul_f32 v[52:53], v[112:113], v[112:113]
	v_pk_mul_f32 v[50:51], v[26:27], v[50:51]
	v_pk_fma_f32 v[52:53], v[110:111], v[110:111], v[52:53]
	v_pk_mul_f32 v[56:57], v[10:11], v[56:57]
	v_add_f32_e32 v52, v52, v60
	v_add_f32_e32 v52, v53, v52
	ds_bpermute_b32 v53, v44, v52
	v_pk_mul_f32 v[58:59], v[18:19], v[58:59]
	v_pk_mul_f32 v[64:65], v[14:15], v[104:105]
	s_waitcnt lgkmcnt(0)
	v_add_f32_e32 v52, v52, v53
	ds_bpermute_b32 v53, v45, v52
	s_waitcnt lgkmcnt(0)
	v_add_f32_e32 v52, v52, v53
	ds_bpermute_b32 v53, v46, v52
	s_waitcnt lgkmcnt(0)
	v_add_f32_e32 v52, v52, v53
	ds_bpermute_b32 v53, v47, v52
	s_waitcnt lgkmcnt(0)
	v_add_f32_e32 v52, v52, v53
	ds_bpermute_b32 v53, v48, v52
	s_waitcnt lgkmcnt(0)
	v_add_f32_e32 v52, v52, v53
	ds_bpermute_b32 v53, v49, v52
	s_waitcnt lgkmcnt(0)
	v_add_f32_e32 v52, v52, v53
	v_fmamk_f32 v52, v52, 0x3a000000, v226
	v_cmp_gt_f32_e32 vcc, s93, v52
	v_mul_f32_e32 v53, 0x4f800000, v52
	s_nop 0
	v_cndmask_b32_e32 v52, v52, v53, vcc
	v_sqrt_f32_e32 v53, v52
	s_nop 0
	v_add_u32_e32 v60, -1, v53
	v_fma_f32 v61, -v60, v53, v52
	v_cmp_ge_f32_e64 s[38:39], 0, v61
	v_add_u32_e32 v61, 1, v53
	s_nop 0
	v_cndmask_b32_e64 v60, v53, v60, s[38:39]
	v_fma_f32 v53, -v61, v53, v52
	v_cmp_lt_f32_e64 s[38:39], 0, v53
	s_nop 1
	v_cndmask_b32_e64 v53, v60, v61, s[38:39]
	v_mul_f32_e32 v60, 0x37800000, v53
	v_cndmask_b32_e32 v53, v53, v60, vcc
	v_cmp_class_f32_e32 vcc, v52, v227
	s_nop 1
	v_cndmask_b32_e32 v52, v53, v52, vcc
	v_div_scale_f32 v53, s[6:7], v52, v52, 1.0
	v_rcp_f32_e32 v60, v53
	s_nop 0
	v_fma_f32 v61, -v53, v60, 1.0
	v_fmac_f32_e32 v60, v61, v60
	v_div_scale_f32 v61, vcc, 1.0, v52, 1.0
	v_mul_f32_e32 v62, v61, v60
	v_fma_f32 v63, -v53, v62, v61
	v_fmac_f32_e32 v62, v63, v60
	v_fma_f32 v53, -v53, v62, v61
	v_div_fmas_f32 v53, v53, v60, v62
	v_div_fixup_f32 v114, v53, v52, 1.0
	v_pk_mul_f32 v[60:61], v[24:25], v[90:91]
	v_pk_fma_f32 v[52:53], v[50:51], v[114:115], v[42:43] op_sel_hi:[1,0,1]
	v_pk_mul_f32 v[42:43], v[0:1], v[92:93]
	v_pk_fma_f32 v[50:51], v[60:61], v[114:115], v[38:39] op_sel_hi:[1,0,1]
	v_pk_mul_f32 v[38:39], v[2:3], v[94:95]
	v_pk_fma_f32 v[36:37], v[42:43], v[114:115], v[36:37] op_sel_hi:[1,0,1]
	v_pk_mul_f32 v[42:43], v[6:7], v[54:55]
	v_pk_mul_f32 v[54:55], v[8:9], v[98:99]
	v_pk_fma_f32 v[38:39], v[38:39], v[114:115], v[40:41] op_sel_hi:[1,0,1]
	v_pk_mul_f32 v[40:41], v[4:5], v[96:97]
	v_pk_fma_f32 v[54:55], v[54:55], v[114:115], v[70:71] op_sel_hi:[1,0,1]
	v_pk_mul_f32 v[62:63], v[16:17], v[100:101]
	v_mov_b32_e32 v70, v110
	v_mov_b32_e32 v71, v112
	v_mov_b32_e32 v112, v111
	v_pk_fma_f32 v[42:43], v[42:43], v[114:115], v[68:69] op_sel_hi:[1,0,1]
	v_pk_fma_f32 v[40:41], v[40:41], v[114:115], v[66:67] op_sel_hi:[1,0,1]
	v_pk_fma_f32 v[56:57], v[56:57], v[114:115], v[72:73] op_sel_hi:[1,0,1]
	v_pk_fma_f32 v[60:61], v[58:59], v[114:115], v[76:77] op_sel_hi:[1,0,1]
	v_pk_fma_f32 v[58:59], v[62:63], v[114:115], v[74:75] op_sel_hi:[1,0,1]
	v_pk_mul_f32 v[62:63], v[12:13], v[102:103]
	v_pk_mul_f32 v[66:67], v[20:21], v[106:107]
	v_pk_mul_f32 v[68:69], v[22:23], v[108:109]
	v_pk_mul_f32 v[70:71], v[28:29], v[70:71]
	v_pk_mul_f32 v[72:73], v[30:31], v[112:113]
	v_pk_fma_f32 v[64:65], v[64:65], v[114:115], v[80:81] op_sel_hi:[1,0,1]
	v_pk_fma_f32 v[62:63], v[62:63], v[114:115], v[78:79] op_sel_hi:[1,0,1]
	v_pk_fma_f32 v[68:69], v[68:69], v[114:115], v[84:85] op_sel_hi:[1,0,1]
	v_pk_fma_f32 v[66:67], v[66:67], v[114:115], v[82:83] op_sel_hi:[1,0,1]
	v_pk_fma_f32 v[72:73], v[72:73], v[114:115], v[88:89] op_sel_hi:[1,0,1]
	v_pk_fma_f32 v[70:71], v[70:71], v[114:115], v[86:87] op_sel_hi:[1,0,1]
	global_store_dwordx4 v[32:33], v[50:53], off offset:-4096
	global_store_dwordx4 v[32:33], v[36:39], off offset:-4080
	global_store_dwordx4 v[32:33], v[40:43], off offset:-2048
	global_store_dwordx4 v[32:33], v[54:57], off offset:-2032
	global_store_dwordx4 v[32:33], v[58:61], off
	global_store_dwordx4 v[32:33], v[62:65], off offset:16
	global_store_dwordx4 v[32:33], v[66:69], off offset:2048
	global_store_dwordx4 v[32:33], v[70:73], off offset:2064
	v_lshl_add_u64 v[32:33], v[32:33], 0, s[22:23]
	s_cbranch_scc0 .LBB0_797
